# baseline (speedup 1.0000x reference)
.LBB0_1102:
	s_or_b64 exec, exec, s[14:15]
	v_lshlrev_b32_e32 v98, 2, v66
	v_mov_b32_e32 v99, v96
	v_lshl_add_u64 v[2:3], v[2:3], 0, v[98:99]
	s_movk_i32 s14, 0x1000
	global_load_dwordx4 v[60:63], v[2:3], off
	global_load_dwordx4 v[56:59], v[2:3], off offset:1024
	global_load_dwordx4 v[52:55], v[2:3], off offset:2048
	global_load_dwordx4 v[48:51], v[2:3], off offset:3072
	v_add_co_u32_e32 v2, vcc, s14, v2
	v_add_u32_e32 v4, 0xfffff000, v64
	s_nop 0
	v_addc_co_u32_e32 v3, vcc, 0, v3, vcc
	global_load_dwordx4 v[44:47], v[2:3], off
	global_load_dwordx4 v[40:43], v[2:3], off offset:1024
	s_waitcnt lgkmcnt(0)
	global_load_dwordx4 v[36:39], v[2:3], off offset:2048
	global_load_dwordx4 v[28:31], v[2:3], off offset:3072
	v_lshrrev_b32_e32 v4, 12, v4
	v_add_u32_e32 v4, 1, v4
	v_cmp_lt_i32_e32 vcc, s42, v64
	v_mov_b64_e32 v[2:3], s[10:11]
	global_load_dwordx4 v[112:115], v[68:69], off
	v_cndmask_b32_e32 v4, 0, v4, vcc
	v_add_u32_e32 v4, s34, v4
	v_mad_u64_u32 v[102:103], s[0:1], v4, s36, v[2:3]
	s_mov_b64 s[0:1], 0x2000
	s_nop 0
	v_lshl_add_u64 v[104:105], v[102:103], 0, s[0:1]
	v_lshl_add_u64 v[124:125], v[102:103], 0, v[98:99]
	v_lshl_add_u64 v[2:3], v[104:105], 0, v[98:99]
	global_load_dwordx4 v[116:119], v[124:125], off
	global_load_dwordx4 v[120:123], v[2:3], off
	v_lshl_add_u64 v[0:1], v[0:1], 0, v[98:99]
	v_mov_b32_e32 v85, v96
	v_mov_b32_e32 v87, v96
	v_mov_b32_e32 v89, v96
	v_mov_b32_e32 v91, v96
	v_mov_b32_e32 v93, v96
	s_waitcnt vmcnt(10)
	v_pk_mul_f32 v[4:5], v[60:61], v[60:61]
	s_waitcnt vmcnt(9)
	v_pk_mul_f32 v[8:9], v[56:57], v[56:57]
	v_pk_mul_f32 v[2:3], v[62:63], v[62:63]
	v_pk_mul_f32 v[6:7], v[58:59], v[58:59]
	s_waitcnt vmcnt(8)
	v_pk_mul_f32 v[12:13], v[52:53], v[52:53]
	v_add_f32_e32 v81, v8, v9
	v_add_f32_e32 v83, v4, v5
	v_pk_mul_f32 v[10:11], v[54:55], v[54:55]
	s_waitcnt vmcnt(7)
	v_pk_mul_f32 v[16:17], v[48:49], v[48:49]
	s_waitcnt vmcnt(6)
	v_mov_b32_e32 v24, v45
	s_waitcnt vmcnt(5)
	v_mov_b32_e32 v25, v41
	v_add_f32_e32 v12, v12, v13
	v_add_f32_e32 v6, v81, v6
	v_add_f32_e32 v2, v83, v2
	v_pk_mul_f32 v[14:15], v[50:51], v[50:51]
	v_mov_b32_e32 v22, v44
	v_mov_b32_e32 v23, v40
	v_add_f32_e32 v13, v16, v17
	v_pk_mul_f32 v[4:5], v[24:25], v[24:25]
	v_add_f32_e32 v10, v12, v10
	v_add_f32_e32 v6, v6, v7
	v_add_f32_e32 v7, v2, v3
	v_mov_b32_e32 v18, v46
	v_mov_b32_e32 v19, v42
	s_waitcnt vmcnt(4)
	v_mov_b32_e32 v100, v37
	s_waitcnt vmcnt(3)
	v_mov_b32_e32 v101, v29
	v_add_f32_e32 v12, v13, v14
	v_pk_fma_f32 v[4:5], v[22:23], v[22:23], v[4:5]
	v_add_f32_e32 v10, v10, v11
	v_add_f32_e32 v6, v7, v6
	v_mov_b32_e32 v20, v47
	v_mov_b32_e32 v21, v43
	v_mov_b32_e32 v34, v36
	v_mov_b32_e32 v35, v28
	v_pk_mul_f32 v[8:9], v[100:101], v[100:101]
	v_add_f32_e32 v11, v12, v15
	v_pk_fma_f32 v[2:3], v[18:19], v[18:19], v[4:5]
	v_add_f32_e32 v6, v6, v10
	v_mov_b32_e32 v26, v38
	v_mov_b32_e32 v27, v30
	v_pk_fma_f32 v[8:9], v[34:35], v[34:35], v[8:9]
	v_pk_fma_f32 v[2:3], v[20:21], v[20:21], v[2:3]
	v_add_f32_e32 v6, v6, v11
	v_mov_b32_e32 v32, v39
	v_mov_b32_e32 v33, v31
	v_pk_fma_f32 v[4:5], v[26:27], v[26:27], v[8:9]
	v_add_f32_e32 v2, v6, v2
	v_pk_fma_f32 v[4:5], v[32:33], v[32:33], v[4:5]
	v_add_f32_e32 v2, v2, v3
	v_add_f32_e32 v2, v2, v4
	v_add_f32_e32 v2, v2, v5
	ds_bpermute_b32 v3, v67, v2
	global_load_dwordx4 v[32:35], v[0:1], off
	global_load_dwordx4 v[24:27], v[0:1], off offset:1024
	global_load_dwordx4 v[20:23], v[0:1], off offset:2048
	global_load_dwordx4 v[16:19], v[0:1], off offset:3072
	v_add_co_u32_e32 v0, vcc, s14, v0
	s_waitcnt vmcnt(4)
	v_pk_add_f32 v[120:121], v[120:121], 1.0 op_sel_hi:[1,0]
	s_waitcnt lgkmcnt(0)
	v_add_f32_e32 v2, v2, v3
	ds_bpermute_b32 v3, v97, v2
	v_addc_co_u32_e32 v1, vcc, 0, v1, vcc
	v_pk_add_f32 v[122:123], v[122:123], 1.0 op_sel_hi:[1,0]
	v_mov_b32_e32 v81, v96
	s_waitcnt lgkmcnt(0)
	v_add_f32_e32 v4, v2, v3
	ds_bpermute_b32 v5, v107, v4
	v_lshlrev_b64 v[2:3], 12, v[64:65]
	v_lshl_add_u64 v[100:101], v[78:79], 0, v[2:3]
	v_lshl_add_u64 v[126:127], v[104:105], 0, v[80:81]
	s_waitcnt lgkmcnt(0)
	v_add_f32_e32 v2, v4, v5
	ds_bpermute_b32 v3, v108, v2
	s_waitcnt lgkmcnt(0)
	v_add_f32_e32 v2, v2, v3
	ds_bpermute_b32 v3, v109, v2
	s_waitcnt lgkmcnt(0)
	v_add_f32_e32 v65, v2, v3
	ds_bpermute_b32 v83, v110, v65
	global_load_dwordx4 v[12:15], v[0:1], off
	global_load_dwordx4 v[8:11], v[0:1], off offset:1024
	global_load_dwordx4 v[4:7], v[0:1], off offset:2048
	s_nop 0
	global_load_dwordx4 v[0:3], v[0:1], off offset:3072
	s_waitcnt lgkmcnt(0)
	v_add_f32_e32 v65, v65, v83
	v_fmamk_f32 v65, v65, 0x3a000000, v211
	v_mul_f32_e32 v83, 0x4b800000, v65
	v_cmp_gt_f32_e32 vcc, s33, v65
	s_nop 1
	v_cndmask_b32_e32 v65, v65, v83, vcc
	v_rsq_f32_e32 v65, v65
	s_nop 0
	v_mul_f32_e32 v83, 0x45800000, v65
	v_cndmask_b32_e32 v106, v65, v83, vcc
	v_pk_mul_f32 v[60:61], v[60:61], v[106:107] op_sel_hi:[1,0]
	v_pk_mul_f32 v[62:63], v[62:63], v[106:107] op_sel_hi:[1,0]
	v_pk_mul_f32 v[60:61], v[112:113], v[60:61]
	v_pk_mul_f32 v[62:63], v[114:115], v[62:63]
	v_pk_fma_f32 v[60:61], v[60:61], v[120:121], v[116:117]
	v_pk_fma_f32 v[62:63], v[62:63], v[122:123], v[118:119]
	v_cvt_pk_bf16_f32 v60, v60, v61
	v_cvt_pk_bf16_f32 v61, v62, v63
	global_load_dwordx4 v[128:131], v[68:69], off offset:1024
	global_load_dwordx4 v[132:135], v[126:127], off
	global_load_dwordx4 v[136:139], v[124:125], off offset:1024
	v_mov_b32_e32 v83, v96
	v_lshl_add_u64 v[238:239], v[104:105], 0, v[82:83]
	global_load_dwordx4 v[140:143], v[68:69], off offset:2048
	global_load_dwordx4 v[144:147], v[238:239], off
	global_load_dwordx4 v[148:151], v[124:125], off offset:2048
	v_lshl_add_u64 v[240:241], v[104:105], 0, v[84:85]
	global_load_dwordx4 v[152:155], v[68:69], off offset:3072
	global_load_dwordx4 v[156:159], v[240:241], off
	global_load_dwordx4 v[160:163], v[124:125], off offset:3072
	v_lshl_add_u64 v[242:243], v[104:105], 0, v[86:87]
	global_load_dwordx4 v[164:167], v[70:71], off
	global_load_dwordx4 v[168:171], v[242:243], off
	v_lshl_add_u64 v[244:245], v[102:103], 0, v[86:87]
	global_load_dwordx4 v[172:175], v[244:245], off
	v_lshl_add_u64 v[246:247], v[104:105], 0, v[88:89]
	global_load_dwordx4 v[176:179], v[72:73], off
	global_load_dwordx4 v[180:183], v[246:247], off
	v_lshl_add_u64 v[248:249], v[102:103], 0, v[88:89]
	global_load_dwordx4 v[184:187], v[248:249], off
	v_lshl_add_u64 v[238:239], v[104:105], 0, v[90:91]
	global_load_dwordx4 v[188:191], v[74:75], off
	global_load_dwordx4 v[192:195], v[238:239], off
	v_lshl_add_u64 v[240:241], v[102:103], 0, v[90:91]
	global_load_dwordx4 v[196:199], v[240:241], off
	v_lshl_add_u64 v[242:243], v[102:103], 0, v[92:93]
	v_lshl_add_u64 v[244:245], v[104:105], 0, v[92:93]
	global_load_dwordx4 v[200:203], v[76:77], off
	global_load_dwordx4 v[230:233], v[242:243], off
	global_load_dwordx4 v[234:237], v[244:245], off
	global_store_dwordx2 v[100:101], v[60:61], off
	s_nop 0
	v_pk_mul_f32 v[56:57], v[56:57], v[106:107] op_sel_hi:[1,0]
	v_pk_mul_f32 v[58:59], v[58:59], v[106:107] op_sel_hi:[1,0]
	v_pk_mul_f32 v[52:53], v[52:53], v[106:107] op_sel_hi:[1,0]
	v_pk_mul_f32 v[54:55], v[54:55], v[106:107] op_sel_hi:[1,0]
	v_pk_mul_f32 v[48:49], v[48:49], v[106:107] op_sel_hi:[1,0]
	v_pk_mul_f32 v[50:51], v[50:51], v[106:107] op_sel_hi:[1,0]
	v_pk_mul_f32 v[44:45], v[44:45], v[106:107] op_sel_hi:[1,0]
	v_pk_mul_f32 v[46:47], v[46:47], v[106:107] op_sel_hi:[1,0]
	v_pk_mul_f32 v[40:41], v[40:41], v[106:107] op_sel_hi:[1,0]
	v_pk_mul_f32 v[42:43], v[42:43], v[106:107] op_sel_hi:[1,0]
	v_pk_mul_f32 v[36:37], v[36:37], v[106:107] op_sel_hi:[1,0]
	v_pk_mul_f32 v[38:39], v[38:39], v[106:107] op_sel_hi:[1,0]
	v_pk_mul_f32 v[28:29], v[28:29], v[106:107] op_sel_hi:[1,0]
	v_pk_mul_f32 v[30:31], v[30:31], v[106:107] op_sel_hi:[1,0]
	s_waitcnt vmcnt(21)
	v_pk_mul_f32 v[56:57], v[56:57], v[128:129]
	s_waitcnt vmcnt(20)
	v_pk_add_f32 v[60:61], v[132:133], 1.0 op_sel_hi:[1,0]
	v_pk_mul_f32 v[58:59], v[58:59], v[130:131]
	v_pk_add_f32 v[62:63], v[134:135], 1.0 op_sel_hi:[1,0]
	s_waitcnt vmcnt(19)
	v_pk_fma_f32 v[56:57], v[56:57], v[60:61], v[136:137]
	v_pk_fma_f32 v[58:59], v[58:59], v[62:63], v[138:139]
	v_cvt_pk_bf16_f32 v56, v56, v57
	v_cvt_pk_bf16_f32 v57, v58, v59
	global_store_dwordx2 v[100:101], v[56:57], off offset:512
	s_nop 0
	s_waitcnt vmcnt(19)
	v_pk_mul_f32 v[52:53], v[52:53], v[140:141]
	s_waitcnt vmcnt(18)
	v_pk_add_f32 v[56:57], v[144:145], 1.0 op_sel_hi:[1,0]
	v_pk_mul_f32 v[54:55], v[54:55], v[142:143]
	v_pk_add_f32 v[58:59], v[146:147], 1.0 op_sel_hi:[1,0]
	s_waitcnt vmcnt(17)
	v_pk_fma_f32 v[52:53], v[52:53], v[56:57], v[148:149]
	v_pk_fma_f32 v[54:55], v[54:55], v[58:59], v[150:151]
	v_cvt_pk_bf16_f32 v52, v52, v53
	v_cvt_pk_bf16_f32 v53, v54, v55
	global_store_dwordx2 v[100:101], v[52:53], off offset:1024
	s_nop 0
	v_pk_mul_f32 v[114:115], v[2:3], v[2:3]
	s_waitcnt vmcnt(17)
	v_pk_mul_f32 v[48:49], v[48:49], v[152:153]
	s_waitcnt vmcnt(16)
	v_pk_add_f32 v[52:53], v[156:157], 1.0 op_sel_hi:[1,0]
	v_pk_mul_f32 v[50:51], v[50:51], v[154:155]
	v_pk_add_f32 v[54:55], v[158:159], 1.0 op_sel_hi:[1,0]
	s_waitcnt vmcnt(15)
	v_pk_fma_f32 v[48:49], v[48:49], v[52:53], v[160:161]
	v_pk_fma_f32 v[50:51], v[50:51], v[54:55], v[162:163]
	v_cvt_pk_bf16_f32 v48, v48, v49
	v_cvt_pk_bf16_f32 v49, v50, v51
	global_store_dwordx2 v[100:101], v[48:49], off offset:1536
	s_nop 0
	v_pk_mul_f32 v[62:63], v[18:19], v[18:19]
	v_pk_mul_f32 v[112:113], v[0:1], v[0:1]
	s_waitcnt vmcnt(15)
	v_pk_mul_f32 v[44:45], v[44:45], v[164:165]
	s_waitcnt vmcnt(14)
	v_pk_add_f32 v[48:49], v[168:169], 1.0 op_sel_hi:[1,0]
	v_pk_mul_f32 v[46:47], v[46:47], v[166:167]
	v_pk_add_f32 v[50:51], v[170:171], 1.0 op_sel_hi:[1,0]
	s_waitcnt vmcnt(13)
	v_pk_fma_f32 v[44:45], v[44:45], v[48:49], v[172:173]
	v_pk_fma_f32 v[46:47], v[46:47], v[50:51], v[174:175]
	v_cvt_pk_bf16_f32 v44, v44, v45
	v_cvt_pk_bf16_f32 v45, v46, v47
	global_store_dwordx2 v[100:101], v[44:45], off offset:2048
	s_nop 0
	v_pk_mul_f32 v[58:59], v[34:35], v[34:35]
	v_pk_mul_f32 v[60:61], v[16:17], v[16:17]
	s_waitcnt vmcnt(13)
	v_pk_mul_f32 v[40:41], v[40:41], v[176:177]
	s_waitcnt vmcnt(12)
	v_pk_add_f32 v[44:45], v[180:181], 1.0 op_sel_hi:[1,0]
	v_pk_mul_f32 v[42:43], v[42:43], v[178:179]
	v_pk_add_f32 v[46:47], v[182:183], 1.0 op_sel_hi:[1,0]
	s_waitcnt vmcnt(11)
	v_pk_fma_f32 v[40:41], v[40:41], v[44:45], v[184:185]
	v_pk_fma_f32 v[42:43], v[42:43], v[46:47], v[186:187]
	v_cvt_pk_bf16_f32 v40, v40, v41
	v_cvt_pk_bf16_f32 v41, v42, v43
	global_store_dwordx2 v[100:101], v[40:41], off offset:2560
	s_nop 0
	v_pk_mul_f32 v[56:57], v[32:33], v[32:33]
	v_add_f32_e32 v116, v60, v61
	v_add_f32_e32 v95, v56, v57
	v_add_f32_e32 v58, v95, v58
	v_pk_mul_f32 v[56:57], v[8:9], v[8:9]
	v_add_f32_e32 v62, v116, v62
	v_pk_mul_f32 v[60:61], v[10:11], v[10:11]
	v_pk_mul_f32 v[102:103], v[4:5], v[4:5]
	v_pk_mul_f32 v[104:105], v[6:7], v[6:7]
	s_waitcnt vmcnt(11)
	v_pk_mul_f32 v[36:37], v[36:37], v[188:189]
	s_waitcnt vmcnt(10)
	v_pk_add_f32 v[40:41], v[192:193], 1.0 op_sel_hi:[1,0]
	v_pk_mul_f32 v[38:39], v[38:39], v[190:191]
	v_pk_add_f32 v[42:43], v[194:195], 1.0 op_sel_hi:[1,0]
	s_waitcnt vmcnt(9)
	v_pk_fma_f32 v[36:37], v[36:37], v[40:41], v[196:197]
	v_pk_fma_f32 v[38:39], v[38:39], v[42:43], v[198:199]
	v_cvt_pk_bf16_f32 v36, v36, v37
	v_cvt_pk_bf16_f32 v37, v38, v39
	global_store_dwordx2 v[100:101], v[36:37], off offset:3072
	v_pk_mul_f32 v[36:37], v[24:25], v[24:25]
	v_pk_mul_f32 v[50:51], v[26:27], v[26:27]
	v_pk_mul_f32 v[52:53], v[20:21], v[20:21]
	v_add_f32_e32 v65, v36, v37
	v_pk_mul_f32 v[54:55], v[22:23], v[22:23]
	v_add_f32_e32 v111, v52, v53
	v_add_f32_e32 v50, v65, v50
	v_pk_mul_f32 v[36:37], v[12:13], v[12:13]
	v_add_f32_e32 v54, v111, v54
	v_add_f32_e32 v50, v50, v51
	v_add_f32_e32 v51, v58, v59
	v_pk_mul_f32 v[52:53], v[14:15], v[14:15]
	v_add_f32_e32 v54, v54, v55
	v_add_f32_e32 v36, v36, v37
	v_add_f32_e32 v50, v51, v50
	v_add_f32_e32 v55, v62, v63
	v_add_f32_e32 v37, v56, v57
	v_add_f32_e32 v36, v36, v52
	v_add_f32_e32 v50, v50, v54
	v_add_f32_e32 v56, v102, v103
	v_add_f32_e32 v37, v37, v60
	v_add_f32_e32 v36, v36, v53
	v_add_f32_e32 v50, v50, v55
	v_add_f32_e32 v57, v112, v113
	v_add_f32_e32 v51, v56, v104
	v_add_f32_e32 v37, v37, v61
	v_add_f32_e32 v36, v50, v36
	v_add_f32_e32 v52, v57, v114
	v_add_f32_e32 v51, v51, v105
	v_add_f32_e32 v36, v36, v37
	v_add_f32_e32 v52, v52, v115
	v_add_f32_e32 v36, v36, v51
	v_add_f32_e32 v36, v36, v52
	ds_bpermute_b32 v37, v67, v36
	s_waitcnt lgkmcnt(0)
	v_add_f32_e32 v36, v36, v37
	ds_bpermute_b32 v37, v97, v36
	s_waitcnt lgkmcnt(0)
	v_add_f32_e32 v36, v36, v37
	ds_bpermute_b32 v37, v107, v36
	s_waitcnt lgkmcnt(0)
	v_add_f32_e32 v36, v36, v37
	ds_bpermute_b32 v37, v108, v36
	s_waitcnt lgkmcnt(0)
	v_add_f32_e32 v36, v36, v37
	ds_bpermute_b32 v37, v109, v36
	s_waitcnt lgkmcnt(0)
	v_add_f32_e32 v36, v36, v37
	ds_bpermute_b32 v37, v110, v36
	s_waitcnt vmcnt(9)
	v_pk_mul_f32 v[28:29], v[28:29], v[200:201]
	v_pk_mul_f32 v[30:31], v[30:31], v[202:203]
	s_waitcnt vmcnt(7)
	v_pk_add_f32 v[38:39], v[234:235], 1.0 op_sel_hi:[1,0]
	v_pk_add_f32 v[40:41], v[236:237], 1.0 op_sel_hi:[1,0]
	v_pk_fma_f32 v[28:29], v[28:29], v[38:39], v[230:231]
	v_pk_fma_f32 v[30:31], v[30:31], v[40:41], v[232:233]
	v_cvt_pk_bf16_f32 v28, v28, v29
	v_cvt_pk_bf16_f32 v29, v30, v31
	global_store_dwordx2 v[100:101], v[28:29], off offset:3584
	s_and_saveexec_b64 s[0:1], s[4:5]
	s_cbranch_execz .LBB0_1076
	s_waitcnt lgkmcnt(0)
	v_add_f32_e32 v28, v36, v37
	v_fmamk_f32 v28, v28, 0x3a000000, v211
	v_cmp_gt_f32_e32 vcc, s33, v28
	v_mul_f32_e32 v29, 0x4b800000, v28
	v_mov_b64_e32 v[30:31], s[10:11]
	v_cndmask_b32_e32 v28, v28, v29, vcc
	v_rsq_f32_e32 v28, v28
	v_ashrrev_i32_e32 v95, 31, v94
	v_lshlrev_b64 v[52:53], 12, v[94:95]
	v_mul_f32_e32 v29, 0x45800000, v28
	v_cndmask_b32_e32 v28, v28, v29, vcc
	v_add_u32_e32 v29, 0xfffff000, v94
	v_lshrrev_b32_e32 v29, 12, v29
	v_add_u32_e32 v29, 1, v29
	v_cmp_lt_i32_e32 vcc, s42, v94
	s_nop 1
	v_cndmask_b32_e32 v29, 0, v29, vcc
	v_add_u32_e32 v29, s34, v29
	v_mad_u64_u32 v[36:37], s[4:5], v29, s36, v[30:31]
	s_mov_b64 s[4:5], 0x2000
	s_nop 0
	v_lshl_add_u64 v[30:31], v[36:37], 0, s[4:5]
	v_lshl_add_u64 v[48:49], v[30:31], 0, v[98:99]
	v_lshl_add_u64 v[38:39], v[36:37], 0, v[98:99]
	global_load_dwordx4 v[40:43], v[68:69], off
	global_load_dwordx4 v[44:47], v[38:39], off
	s_nop 0
	global_load_dwordx4 v[48:51], v[48:49], off
	v_pk_mul_f32 v[32:33], v[32:33], v[28:29] op_sel_hi:[1,0]
	v_pk_mul_f32 v[34:35], v[34:35], v[28:29] op_sel_hi:[1,0]
	v_pk_mul_f32 v[24:25], v[24:25], v[28:29] op_sel_hi:[1,0]
	v_pk_mul_f32 v[26:27], v[26:27], v[28:29] op_sel_hi:[1,0]
	v_pk_mul_f32 v[20:21], v[20:21], v[28:29] op_sel_hi:[1,0]
	v_pk_mul_f32 v[22:23], v[22:23], v[28:29] op_sel_hi:[1,0]
	v_pk_mul_f32 v[16:17], v[16:17], v[28:29] op_sel_hi:[1,0]
	v_pk_mul_f32 v[18:19], v[18:19], v[28:29] op_sel_hi:[1,0]
	v_pk_mul_f32 v[12:13], v[12:13], v[28:29] op_sel_hi:[1,0]
	v_pk_mul_f32 v[14:15], v[14:15], v[28:29] op_sel_hi:[1,0]
	v_pk_mul_f32 v[8:9], v[8:9], v[28:29] op_sel_hi:[1,0]
	v_pk_mul_f32 v[10:11], v[10:11], v[28:29] op_sel_hi:[1,0]
	v_pk_mul_f32 v[4:5], v[4:5], v[28:29] op_sel_hi:[1,0]
	v_pk_mul_f32 v[6:7], v[6:7], v[28:29] op_sel_hi:[1,0]
	v_pk_mul_f32 v[0:1], v[0:1], v[28:29] op_sel_hi:[1,0]
	v_pk_mul_f32 v[2:3], v[2:3], v[28:29] op_sel_hi:[1,0]
	s_waitcnt vmcnt(2)
	v_pk_mul_f32 v[32:33], v[32:33], v[40:41]
	v_pk_mul_f32 v[34:35], v[34:35], v[42:43]
	s_waitcnt vmcnt(0)
	v_pk_add_f32 v[40:41], v[48:49], 1.0 op_sel_hi:[1,0]
	s_nop 0
	v_pk_fma_f32 v[32:33], v[32:33], v[40:41], v[44:45]
	v_pk_add_f32 v[40:41], v[50:51], 1.0 op_sel_hi:[1,0]
	s_nop 0
	v_pk_fma_f32 v[34:35], v[34:35], v[40:41], v[46:47]
	v_cvt_pk_bf16_f32 v40, v32, v33
	v_cvt_pk_bf16_f32 v41, v34, v35
	v_lshl_add_u64 v[32:33], v[78:79], 0, v[52:53]
	v_lshl_add_u64 v[238:239], v[30:31], 0, v[80:81]
	global_load_dwordx4 v[128:131], v[68:69], off offset:1024
	global_load_dwordx4 v[132:135], v[38:39], off offset:1024
	global_load_dwordx4 v[136:139], v[238:239], off
	v_lshl_add_u64 v[240:241], v[30:31], 0, v[82:83]
	global_load_dwordx4 v[140:143], v[68:69], off offset:2048
	global_load_dwordx4 v[144:147], v[38:39], off offset:2048
	global_load_dwordx4 v[148:151], v[240:241], off
	v_lshl_add_u64 v[242:243], v[30:31], 0, v[84:85]
	global_load_dwordx4 v[152:155], v[68:69], off offset:3072
	global_load_dwordx4 v[156:159], v[38:39], off offset:3072
	global_load_dwordx4 v[160:163], v[242:243], off
	v_lshl_add_u64 v[244:245], v[36:37], 0, v[86:87]
	v_lshl_add_u64 v[246:247], v[30:31], 0, v[86:87]
	global_load_dwordx4 v[164:167], v[70:71], off
	global_load_dwordx4 v[168:171], v[244:245], off
	global_load_dwordx4 v[172:175], v[246:247], off
	v_lshl_add_u64 v[248:249], v[36:37], 0, v[88:89]
	v_lshl_add_u64 v[238:239], v[30:31], 0, v[88:89]
	global_load_dwordx4 v[176:179], v[72:73], off
	global_load_dwordx4 v[180:183], v[248:249], off
	global_load_dwordx4 v[184:187], v[238:239], off
	v_lshl_add_u64 v[240:241], v[36:37], 0, v[90:91]
	v_lshl_add_u64 v[242:243], v[30:31], 0, v[90:91]
	global_load_dwordx4 v[188:191], v[74:75], off
	global_load_dwordx4 v[192:195], v[240:241], off
	global_load_dwordx4 v[196:199], v[242:243], off
	v_lshl_add_u64 v[244:245], v[36:37], 0, v[92:93]
	v_lshl_add_u64 v[246:247], v[30:31], 0, v[92:93]
	global_load_dwordx4 v[200:203], v[76:77], off
	global_load_dwordx4 v[230:233], v[244:245], off
	global_load_dwordx4 v[234:237], v[246:247], off
	global_store_dwordx2 v[32:33], v[40:41], off
	s_waitcnt vmcnt(21)
	v_pk_mul_f32 v[24:25], v[24:25], v[128:129]
	v_pk_mul_f32 v[26:27], v[26:27], v[130:131]
	s_waitcnt vmcnt(19)
	v_pk_add_f32 v[34:35], v[136:137], 1.0 op_sel_hi:[1,0]
	s_nop 0
	v_pk_fma_f32 v[24:25], v[24:25], v[34:35], v[132:133]
	v_pk_add_f32 v[34:35], v[138:139], 1.0 op_sel_hi:[1,0]
	v_cvt_pk_bf16_f32 v24, v24, v25
	v_pk_fma_f32 v[26:27], v[26:27], v[34:35], v[134:135]
	v_cvt_pk_bf16_f32 v25, v26, v27
	global_store_dwordx2 v[32:33], v[24:25], off offset:512
	s_nop 0
	s_waitcnt vmcnt(19)
	v_pk_mul_f32 v[20:21], v[20:21], v[140:141]
	v_pk_mul_f32 v[22:23], v[22:23], v[142:143]
	s_waitcnt vmcnt(17)
	v_pk_add_f32 v[24:25], v[148:149], 1.0 op_sel_hi:[1,0]
	s_nop 0
	v_pk_fma_f32 v[20:21], v[20:21], v[24:25], v[144:145]
	v_pk_add_f32 v[24:25], v[150:151], 1.0 op_sel_hi:[1,0]
	v_cvt_pk_bf16_f32 v20, v20, v21
	v_pk_fma_f32 v[22:23], v[22:23], v[24:25], v[146:147]
	s_nop 0
	v_cvt_pk_bf16_f32 v21, v22, v23
	global_store_dwordx2 v[32:33], v[20:21], off offset:1024
	s_nop 0
	s_nop 0
	s_waitcnt vmcnt(17)
	v_pk_mul_f32 v[16:17], v[16:17], v[152:153]
	v_pk_mul_f32 v[18:19], v[18:19], v[154:155]
	s_waitcnt vmcnt(15)
	v_pk_add_f32 v[20:21], v[160:161], 1.0 op_sel_hi:[1,0]
	s_nop 0
	v_pk_fma_f32 v[16:17], v[16:17], v[20:21], v[156:157]
	v_pk_add_f32 v[20:21], v[162:163], 1.0 op_sel_hi:[1,0]
	v_cvt_pk_bf16_f32 v16, v16, v17
	v_pk_fma_f32 v[18:19], v[18:19], v[20:21], v[158:159]
	v_cvt_pk_bf16_f32 v17, v18, v19
	global_store_dwordx2 v[32:33], v[16:17], off offset:1536
	s_nop 0
	s_nop 0
	s_waitcnt vmcnt(15)
	v_pk_mul_f32 v[12:13], v[12:13], v[164:165]
	v_pk_mul_f32 v[14:15], v[14:15], v[166:167]
	s_waitcnt vmcnt(13)
	v_pk_add_f32 v[16:17], v[172:173], 1.0 op_sel_hi:[1,0]
	s_nop 0
	v_pk_fma_f32 v[12:13], v[12:13], v[16:17], v[168:169]
	v_pk_add_f32 v[16:17], v[174:175], 1.0 op_sel_hi:[1,0]
	v_cvt_pk_bf16_f32 v12, v12, v13
	v_pk_fma_f32 v[14:15], v[14:15], v[16:17], v[170:171]
	v_cvt_pk_bf16_f32 v13, v14, v15
	global_store_dwordx2 v[32:33], v[12:13], off offset:2048
	s_nop 0
	s_nop 0
	s_waitcnt vmcnt(13)
	v_pk_mul_f32 v[8:9], v[8:9], v[176:177]
	v_pk_mul_f32 v[10:11], v[10:11], v[178:179]
	s_waitcnt vmcnt(11)
	v_pk_add_f32 v[12:13], v[184:185], 1.0 op_sel_hi:[1,0]
	s_nop 0
	v_pk_fma_f32 v[8:9], v[8:9], v[12:13], v[180:181]
	v_pk_add_f32 v[12:13], v[186:187], 1.0 op_sel_hi:[1,0]
	v_cvt_pk_bf16_f32 v8, v8, v9
	v_pk_fma_f32 v[10:11], v[10:11], v[12:13], v[182:183]
	v_cvt_pk_bf16_f32 v9, v10, v11
	global_store_dwordx2 v[32:33], v[8:9], off offset:2560
	s_nop 0
	s_nop 0
	s_waitcnt vmcnt(11)
	v_pk_mul_f32 v[4:5], v[4:5], v[188:189]
	v_pk_mul_f32 v[6:7], v[6:7], v[190:191]
	s_waitcnt vmcnt(9)
	v_pk_add_f32 v[8:9], v[196:197], 1.0 op_sel_hi:[1,0]
	s_nop 0
	v_pk_fma_f32 v[4:5], v[4:5], v[8:9], v[192:193]
	v_pk_add_f32 v[8:9], v[198:199], 1.0 op_sel_hi:[1,0]
	v_cvt_pk_bf16_f32 v4, v4, v5
	v_pk_fma_f32 v[6:7], v[6:7], v[8:9], v[194:195]
	v_cvt_pk_bf16_f32 v5, v6, v7
	global_store_dwordx2 v[32:33], v[4:5], off offset:3072
	s_nop 0
	s_nop 0
	s_waitcnt vmcnt(9)
	v_pk_mul_f32 v[0:1], v[0:1], v[200:201]
	v_pk_mul_f32 v[2:3], v[2:3], v[202:203]
	s_waitcnt vmcnt(7)
	v_pk_add_f32 v[4:5], v[234:235], 1.0 op_sel_hi:[1,0]
	s_nop 0
	v_pk_fma_f32 v[0:1], v[0:1], v[4:5], v[230:231]
	v_pk_add_f32 v[4:5], v[236:237], 1.0 op_sel_hi:[1,0]
	v_cvt_pk_bf16_f32 v0, v0, v1
	v_pk_fma_f32 v[2:3], v[2:3], v[4:5], v[232:233]
	s_nop 0
	v_cvt_pk_bf16_f32 v1, v2, v3
	global_store_dwordx2 v[32:33], v[0:1], off offset:3584
	s_branch .LBB0_1076
